# five grid barriers between the row-partitioned phases (7-9, 9-11, 12-13, 13-15, 15-16) replaced by barriers of the 32 workgroups with the same blockIdx&7 (one XCD, placement checked at run time with f
# baseline (speedup 1.0000x reference)
.LBB0_2170:
	s_cmp_lt_i32 s87, 6
	s_cselect_b64 s[0:1], -1, 0
	s_xor_b64 s[2:3], s[66:67], -1
	s_or_b64 s[0:1], s[2:3], s[0:1]
	s_and_b64 vcc, exec, s[0:1]
	s_cbranch_vccnz .LBB0_2224
	s_waitcnt vmcnt(0)
	s_waitcnt vmcnt(0)
	s_barrier
	s_mov_b64 s[0:1], exec
	v_readlane_b32 s2, v251, 1
	v_readlane_b32 s3, v251, 2
	s_and_b64 s[2:3], s[0:1], s[2:3]
	s_mov_b64 exec, s[2:3]
	s_cbranch_execz .LBB0_2223
	s_and_b32 s2, s90, 7
	s_cmp_lg_u32 s2, s84
	s_cselect_b32 s2, 1, 0
	s_cmp_lg_u32 s92, 0x100
	s_cselect_b32 s3, 1, 0
	s_or_b32 s2, s2, s3
	s_cmp_eq_u32 s2, 0
	s_cbranch_scc1 .Lplc_ok
	v_mov_b32_e32 v0, 0x3e00
	v_mov_b32_e32 v2, 1
	global_atomic_add v0, v2, s[96:97]
	s_waitcnt vmcnt(0)
.Lplc_ok:
	s_add_i32 s2, 0, 0x23fc0
	v_mov_b32_e32 v0, s2
	s_waitcnt vmcnt(0) expcnt(0) lgkmcnt(0)
	buffer_inv sc1
	ds_read_b32 v2, v0
	s_add_i32 s2, 0, 0x23fc4
	v_mov_b32_e32 v0, s2
	ds_read_b32 v0, v0
	s_waitcnt lgkmcnt(1)
	v_cmp_ne_u32_e32 vcc, 0, v2
	s_cbranch_vccnz .LBB0_2187
	v_readlane_b32 s2, v251, 0
	s_mul_i32 s16, s93, s2
	s_add_u32 s2, s96, 0x1000
	s_addc_u32 s3, s97, 0
	s_add_u32 s4, s96, 0x1100
	s_addc_u32 s5, s97, 0
	s_add_u32 s6, s96, 0x1200
	s_addc_u32 s7, s97, 0
	s_add_u32 s8, s96, 0x1300
	s_mul_i32 s16, s16, s92
	s_addc_u32 s9, s97, 0
	s_mov_b32 s17, 1
	v_mov_b32_e32 v16, 0
	s_branch .LBB0_2175

.LBB0_2265:
	s_cmp_lt_i32 s87, 9
	s_cselect_b64 s[2:3], -1, 0
	s_xor_b64 s[0:1], s[0:1], -1
	s_or_b64 s[0:1], s[0:1], s[2:3]
	s_and_b64 vcc, exec, s[0:1]
	s_cbranch_vccnz .LBB0_2319
	s_waitcnt vmcnt(0)
	s_waitcnt vmcnt(0)
	s_barrier
	s_mov_b64 s[0:1], exec
	v_readlane_b32 s2, v251, 1
	v_readlane_b32 s3, v251, 2
	s_and_b64 s[2:3], s[0:1], s[2:3]
	s_mov_b64 exec, s[2:3]
	s_cbranch_execz .LBB0_2318
	s_waitcnt vmcnt(0) expcnt(0) lgkmcnt(0)
	buffer_inv sc1
	s_and_b32 s2, s90, 7
	s_lshl_b32 s2, s2, 8
	s_add_i32 s2, s2, 0x3600
	v_mov_b32_e32 v0, s2
	v_mov_b32_e32 v2, 1
	global_atomic_add v0, v0, v2, s[96:97] sc0
	s_nop 0
	v_mov_b32_e32 v2, 0x3e00
	global_load_dword v2, v2, s[96:97] sc1
	s_waitcnt vmcnt(0)
	v_readfirstlane_b32 s3, v2
	v_readfirstlane_b32 vcc_lo, v0
	s_cmp_lg_u32 s3, 0
	s_cbranch_scc1 .Lgb_orig0
	s_or_b32 s3, vcc_lo, 31
	s_cmp_eq_u32 s3, vcc_lo
	s_cbranch_scc1 .Lgb_done0
	s_add_i32 s3, s3, 1
	s_mov_b32 vcc_hi, 0
	v_mov_b32_e32 v0, s2
.Lgb_poll0:
	global_load_dword v2, v0, s[96:97] sc1
	s_waitcnt vmcnt(0)
	v_readfirstlane_b32 vcc_lo, v2
	s_sub_i32 vcc_lo, vcc_lo, s3
	s_cmp_ge_i32 vcc_lo, 0
	s_cbranch_scc1 .Lgb_done0
	s_add_i32 vcc_hi, vcc_hi, 1
	s_cmp_lt_u32 vcc_hi, 0x40000
	s_cbranch_scc0 .Lgb_done0
	s_sleep 1
	s_branch .Lgb_poll0

.LBB0_2358:
	s_cmp_lt_i32 s87, 11
	s_cselect_b64 s[2:3], -1, 0
	s_xor_b64 s[0:1], s[0:1], -1
	s_or_b64 s[0:1], s[0:1], s[2:3]
	s_and_b64 vcc, exec, s[0:1]
	s_cbranch_vccnz .LBB0_2412
	s_waitcnt vmcnt(0)
	s_waitcnt vmcnt(0)
	s_barrier
	s_mov_b64 s[0:1], exec
	v_readlane_b32 s2, v251, 1
	v_readlane_b32 s3, v251, 2
	s_and_b64 s[2:3], s[0:1], s[2:3]
	s_mov_b64 exec, s[2:3]
	s_cbranch_execz .LBB0_2411
	s_waitcnt vmcnt(0) expcnt(0) lgkmcnt(0)
	buffer_inv sc1
	s_and_b32 s2, s90, 7
	s_lshl_b32 s2, s2, 8
	s_add_i32 s2, s2, 0x3600
	v_mov_b32_e32 v0, s2
	v_mov_b32_e32 v2, 1
	global_atomic_add v0, v0, v2, s[96:97] sc0
	s_nop 0
	v_mov_b32_e32 v2, 0x3e00
	global_load_dword v2, v2, s[96:97] sc1
	s_waitcnt vmcnt(0)
	v_readfirstlane_b32 s3, v2
	v_readfirstlane_b32 vcc_lo, v0
	s_cmp_lg_u32 s3, 0
	s_cbranch_scc1 .Lgb_orig1
	s_or_b32 s3, vcc_lo, 31
	s_cmp_eq_u32 s3, vcc_lo
	s_cbranch_scc1 .Lgb_done1
	s_add_i32 s3, s3, 1
	s_mov_b32 vcc_hi, 0
	v_mov_b32_e32 v0, s2

.LBB0_2496:
	s_cmp_gt_i32 s87, 13
	s_cselect_b64 s[2:3], -1, 0
	s_and_b64 s[0:1], s[0:1], s[2:3]
	s_andn2_b64 vcc, exec, s[0:1]
	s_cbranch_vccnz .LBB0_2550
	s_waitcnt vmcnt(0)
	s_waitcnt vmcnt(0)
	s_barrier
	s_mov_b64 s[0:1], exec
	v_readlane_b32 s4, v251, 1
	v_readlane_b32 s5, v251, 2
	s_and_b64 s[4:5], s[0:1], s[4:5]
	s_mov_b64 exec, s[4:5]
	s_cbranch_execz .LBB0_2549
	s_waitcnt vmcnt(0) expcnt(0) lgkmcnt(0)
	buffer_inv sc1
	s_and_b32 s4, s90, 7
	s_lshl_b32 s4, s4, 8
	s_add_i32 s4, s4, 0x3600
	v_mov_b32_e32 v0, s4
	v_mov_b32_e32 v2, 1
	global_atomic_add v0, v0, v2, s[96:97] sc0
	s_nop 0
	v_mov_b32_e32 v2, 0x3e00
	global_load_dword v2, v2, s[96:97] sc1
	s_waitcnt vmcnt(0)
	v_readfirstlane_b32 s5, v2
	v_readfirstlane_b32 vcc_lo, v0
	s_cmp_lg_u32 s5, 0
	s_cbranch_scc1 .Lgb_orig2
	s_or_b32 s5, vcc_lo, 31
	s_cmp_eq_u32 s5, vcc_lo
	s_cbranch_scc1 .Lgb_done2
	s_add_i32 s5, s5, 1
	s_mov_b32 vcc_hi, 0
	v_mov_b32_e32 v0, s4
.Lgb_poll2:
	global_load_dword v2, v0, s[96:97] sc1
	s_waitcnt vmcnt(0)
	v_readfirstlane_b32 vcc_lo, v2
	s_sub_i32 vcc_lo, vcc_lo, s5
	s_cmp_ge_i32 vcc_lo, 0
	s_cbranch_scc1 .Lgb_done2
	s_add_i32 vcc_hi, vcc_hi, 1
	s_cmp_lt_u32 vcc_hi, 0x40000
	s_cbranch_scc0 .Lgb_done2
	s_sleep 1
	s_branch .Lgb_poll2

.Lgb_orig2:
	s_add_i32 s4, 0, 0x23fc0
	v_mov_b32_e32 v0, s4
	s_waitcnt vmcnt(0) expcnt(0) lgkmcnt(0)
	buffer_inv sc1
	ds_read_b32 v2, v0
	s_add_i32 s4, 0, 0x23fc4
	v_mov_b32_e32 v0, s4
	ds_read_b32 v0, v0
	s_waitcnt lgkmcnt(1)
	v_cmp_ne_u32_e32 vcc, 0, v2
	s_cbranch_vccnz .LBB0_2513
	v_readlane_b32 s4, v251, 0
	s_mul_i32 s18, s93, s4
	s_add_u32 s4, s96, 0x1000
	s_addc_u32 s5, s97, 0
	s_add_u32 s6, s96, 0x1100
	s_addc_u32 s7, s97, 0
	s_add_u32 s8, s96, 0x1200
	s_addc_u32 s9, s97, 0
	s_add_u32 s10, s96, 0x1300
	s_mul_i32 s18, s18, s92
	s_addc_u32 s11, s97, 0
	s_mov_b32 s19, 1
	v_mov_b32_e32 v16, 0
	s_branch .LBB0_2501

.LBB0_2589:
	s_cmp_lt_i32 s87, 15
	s_cselect_b64 s[2:3], -1, 0
	s_xor_b64 s[0:1], s[0:1], -1
	s_or_b64 s[0:1], s[0:1], s[2:3]
	s_and_b64 vcc, exec, s[0:1]
	s_cbranch_vccnz .LBB0_2643
	s_waitcnt vmcnt(0)
	s_waitcnt vmcnt(0)
	s_barrier
	s_mov_b64 s[0:1], exec
	v_readlane_b32 s2, v251, 1
	v_readlane_b32 s3, v251, 2
	s_and_b64 s[2:3], s[0:1], s[2:3]
	s_mov_b64 exec, s[2:3]
	s_cbranch_execz .LBB0_2642
	s_waitcnt vmcnt(0) expcnt(0) lgkmcnt(0)
	buffer_inv sc1
	s_and_b32 s2, s90, 7
	s_lshl_b32 s2, s2, 8
	s_add_i32 s2, s2, 0x3600
	v_mov_b32_e32 v0, s2
	v_mov_b32_e32 v2, 1
	global_atomic_add v0, v0, v2, s[96:97] sc0
	s_nop 0
	v_mov_b32_e32 v2, 0x3e00
	global_load_dword v2, v2, s[96:97] sc1
	s_waitcnt vmcnt(0)
	v_readfirstlane_b32 s3, v2
	v_readfirstlane_b32 vcc_lo, v0
	s_cmp_lg_u32 s3, 0
	s_cbranch_scc1 .Lgb_orig3
	s_or_b32 s3, vcc_lo, 31
	s_cmp_eq_u32 s3, vcc_lo
	s_cbranch_scc1 .Lgb_done3
	s_add_i32 s3, s3, 1
	s_mov_b32 vcc_hi, 0
	v_mov_b32_e32 v0, s2

.LBB0_2660:
	s_cmp_gt_i32 s87, 16
	s_cselect_b64 s[0:1], -1, 0
	s_and_b64 s[2:3], s[4:5], s[0:1]
	s_andn2_b64 vcc, exec, s[2:3]
	s_cbranch_vccnz .LBB0_2714
	s_waitcnt vmcnt(0)
	s_waitcnt vmcnt(0)
	s_barrier
	s_mov_b64 s[2:3], exec
	v_readlane_b32 s4, v251, 1
	v_readlane_b32 s5, v251, 2
	s_and_b64 s[4:5], s[2:3], s[4:5]
	s_mov_b64 exec, s[4:5]
	s_cbranch_execz .LBB0_2713
	s_waitcnt vmcnt(0) expcnt(0) lgkmcnt(0)
	buffer_inv sc1
	s_and_b32 s4, s90, 7
	s_lshl_b32 s4, s4, 8
	s_add_i32 s4, s4, 0x3600
	v_mov_b32_e32 v0, s4
	v_mov_b32_e32 v2, 1
	global_atomic_add v0, v0, v2, s[96:97] sc0
	s_nop 0
	v_mov_b32_e32 v2, 0x3e00
	global_load_dword v2, v2, s[96:97] sc1
	s_waitcnt vmcnt(0)
	v_readfirstlane_b32 s5, v2
	v_readfirstlane_b32 vcc_lo, v0
	s_cmp_lg_u32 s5, 0
	s_cbranch_scc1 .Lgb_orig4
	s_or_b32 s5, vcc_lo, 31
	s_cmp_eq_u32 s5, vcc_lo
	s_cbranch_scc1 .Lgb_done4
	s_add_i32 s5, s5, 1
	s_mov_b32 vcc_hi, 0
	v_mov_b32_e32 v0, s4
